# speedup vs baseline: 1.0328x; 1.0029x over previous
;   #define WAIT_V(n) asm volatile("s_waitcnt vmcnt(" #n ")":::"memory")
;   #define BAR __builtin_amdgcn_s_barrier()
; template <bool TWO, class MID> ...
;     ...
;   int r0, c0, r1, c1; stage_rc(tid * 16, r0, c0); stage_rc(tid * 16 + 8192, r1, c1);
;   aoff0 = (unsigned)(r0 * lda + c0) * 2u; aoff1 = (unsigned)(r1 * lda + c1) * 2u;
;   boff0 = (unsigned)(r0 * ldb + c0) * 2u; boff1 = (unsigned)(r1 * ldb + c1) * 2u;
;   const char* Ab = (const char*)A + (size_t)brow * lda * 2;
;   const char* Bb = (const char*)Bt + (size_t)bcol * ldb * 2;
;   const char* Ab2 = TWO ? (const char*)A2 + (size_t)brow * lda2 * 2 : nullptr;
;   const char* Bb2 = TWO ? (const char*)Bt2 + (size_t)bcol * ldb2 * 2 : nullptr;
;     ...
;   const int wid = tid >> 6, lane = tid & 63, wr = wid >> 2, wc = wid & 3, fr = lane & 15, fq = lane >> 4;
;   bf16x8 At[4][2], B0[2][2], B1[2][2];
;   const int nt = K / BK;
;   if(wr==1)BAR;
;   if (fresh) WAIT_V(4);
;   BAR;
; template <int EPI>
; __device__ void gemm_phase(const bf16* A, int lda, const bf16* Bt, int K, int N, const Params& p, bool last, bf16* dstb, bf16* shm, unsigned long long* SSQ, int wv, const float* gbias = nullptr) {
;     ...
;     f32x4 acc[2][2][4][2] = {};
.LBB0_168:
	v_and_b32_e32 v5, 15, v2
	v_lshlrev_b32_e32 v7, 2, v2
	v_and_b32_e32 v6, 48, v2
	v_lshlrev_b32_e32 v5, 6, v5
	v_and_b32_e32 v7, 32, v7
	v_lshlrev_b32_e32 v2, 6, v2
	s_mov_b64 s[0:1], src_shared_base
	v_bitop3_b32 v5, v5, v7, v6 bitop3:0x36
	v_lshlrev_b32_e32 v11, 6, v1
	v_lshlrev_b32_e32 v3, 13, v3
	v_and_or_b32 v2, v2, s31, v6
	v_add_u32_e32 v8, s93, v5
	v_add_u32_e32 v148, 0xc000, v138
	v_mov_b32_e32 v149, s1
	v_add_u32_e32 v9, s96, v5
	v_add_u32_e32 v150, s93, v4
	v_mov_b32_e32 v151, s1
	v_mov_b32_e32 v139, s1
	v_add_u32_e32 v152, s96, v4
	v_mov_b32_e32 v153, s1
	v_add_u32_e32 v4, s46, v5
	v_add_u32_e32 v154, 0x4000, v138
	v_mov_b32_e32 v155, s1
	v_add_u32_e32 v10, s92, v5
	v_and_b32_e32 v11, 0x3000, v11
	v_add_u32_e32 v5, 0, v5
	v_xad_u32 v6, v2, v7, 0
	v_or_b32_e32 v7, 0x800, v3
	v_or_b32_e32 v12, 0x1000, v3
	v_or_b32_e32 v13, 0x1800, v3
	v_mov_b32_e32 v2, 0
	s_mov_b32 s9, -2
	v_add_u32_e32 v143, v8, v11
	v_add_u32_e32 v168, v5, v3
	v_add_u32_e32 v167, v6, v7
	v_add_u32_e32 v166, v6, v12
	v_add_u32_e32 v147, v6, v13
	v_add_u32_e32 v141, v9, v11
	v_add_u32_e32 v137, v4, v11
	v_add_u32_e32 v135, v10, v11
	s_mov_b64 s[0:1], s[78:79]
	v_mov_b64_e32 v[2:3], 0
	v_mov_b64_e32 v[4:5], 0
	v_mov_b64_e32 v[6:7], 0
	v_mov_b64_e32 v[8:9], 0
	v_mov_b64_e32 v[10:11], 0
	v_mov_b64_e32 v[12:13], 0
	v_mov_b64_e32 v[14:15], 0
	v_mov_b64_e32 v[16:17], 0
	v_mov_b64_e32 v[18:19], 0
	v_mov_b64_e32 v[20:21], 0
	v_mov_b64_e32 v[22:23], 0
	v_mov_b64_e32 v[24:25], 0
	v_mov_b64_e32 v[26:27], 0
	v_mov_b64_e32 v[28:29], 0
	v_mov_b64_e32 v[30:31], 0
	v_mov_b64_e32 v[32:33], 0
	v_mov_b64_e32 v[34:35], 0
	v_mov_b64_e32 v[36:37], 0
	v_mov_b64_e32 v[38:39], 0
	v_mov_b64_e32 v[40:41], 0
	v_mov_b64_e32 v[42:43], 0
	v_mov_b64_e32 v[44:45], 0
	v_mov_b64_e32 v[46:47], 0
	v_mov_b64_e32 v[48:49], 0
	v_mov_b64_e32 v[50:51], 0
	v_mov_b64_e32 v[52:53], 0
	v_mov_b64_e32 v[54:55], 0
	v_mov_b64_e32 v[56:57], 0
	v_mov_b64_e32 v[58:59], 0
	v_mov_b64_e32 v[60:61], 0
	v_mov_b64_e32 v[62:63], 0
	v_mov_b64_e32 v[64:65], 0
	v_mov_b64_e32 v[66:67], 0
	v_mov_b64_e32 v[68:69], 0
	v_mov_b64_e32 v[70:71], 0
	v_mov_b64_e32 v[72:73], 0
	v_mov_b64_e32 v[74:75], 0
	v_mov_b64_e32 v[76:77], 0
	v_mov_b64_e32 v[78:79], 0
	v_mov_b64_e32 v[80:81], 0
	v_mov_b64_e32 v[82:83], 0
	v_mov_b64_e32 v[84:85], 0
	v_mov_b64_e32 v[86:87], 0
	v_mov_b64_e32 v[88:89], 0
	v_mov_b64_e32 v[90:91], 0
	v_mov_b64_e32 v[92:93], 0
	v_mov_b64_e32 v[94:95], 0
	v_mov_b64_e32 v[96:97], 0
	v_mov_b64_e32 v[98:99], 0
	v_mov_b64_e32 v[100:101], 0
	v_mov_b64_e32 v[102:103], 0
	v_mov_b64_e32 v[104:105], 0
	v_mov_b64_e32 v[106:107], 0
	v_mov_b64_e32 v[108:109], 0
	v_mov_b64_e32 v[110:111], 0
	v_mov_b64_e32 v[112:113], 0
	v_mov_b64_e32 v[114:115], 0
	v_mov_b64_e32 v[116:117], 0
	v_mov_b64_e32 v[118:119], 0
	v_mov_b64_e32 v[120:121], 0
	v_mov_b64_e32 v[122:123], 0
	v_mov_b64_e32 v[124:125], 0
	v_mov_b64_e32 v[126:127], 0
	v_mov_b64_e32 v[128:129], 0
	v_lshl_add_u64 v[156:157], v[148:149], 0, s[2:3]
	v_lshl_add_u64 v[158:159], v[150:151], 0, s[2:3]
	v_lshl_add_u64 v[160:161], v[138:139], 0, s[2:3]
	v_lshl_add_u64 v[162:163], v[152:153], 0, s[2:3]
	v_lshl_add_u64 v[164:165], v[154:155], 0, s[2:3]
	s_barrier

;   #define WAIT_V(n) asm volatile("s_waitcnt vmcnt(" #n ")":::"memory")
;   #define BAR __builtin_amdgcn_s_barrier()
; template <bool TWO, class MID> ...
;     ...
;   int r0, c0, r1, c1; stage_rc(tid * 16, r0, c0); stage_rc(tid * 16 + 8192, r1, c1);
;   aoff0 = (unsigned)(r0 * lda + c0) * 2u; aoff1 = (unsigned)(r1 * lda + c1) * 2u;
;   boff0 = (unsigned)(r0 * ldb + c0) * 2u; boff1 = (unsigned)(r1 * ldb + c1) * 2u;
;   const char* Ab = (const char*)A + (size_t)brow * lda * 2;
;   const char* Bb = (const char*)Bt + (size_t)bcol * ldb * 2;
;   const char* Ab2 = TWO ? (const char*)A2 + (size_t)brow * lda2 * 2 : nullptr;
;   const char* Bb2 = TWO ? (const char*)Bt2 + (size_t)bcol * ldb2 * 2 : nullptr;
;     ...
;   const int wid = tid >> 6, lane = tid & 63, wr = wid >> 2, wc = wid & 3, fr = lane & 15, fq = lane >> 4;
;   bf16x8 At[4][2], B0[2][2], B1[2][2];
;   const int nt = K / BK;
;   if(wr==1)BAR;
;   if (fresh) WAIT_V(4);
;   BAR;
; template <int EPI>
; __device__ void gemm_phase(const bf16* A, int lda, const bf16* Bt, int K, int N, const Params& p, bool last, bf16* dstb, bf16* shm, unsigned long long* SSQ, int wv, const float* gbias = nullptr) {
;     ...
;     f32x4 acc[2][2][4][2] = {};
.LBB0_488:
	v_and_b32_e32 v5, 15, v2
	v_lshlrev_b32_e32 v7, 2, v2
	v_and_b32_e32 v6, 48, v2
	v_lshlrev_b32_e32 v5, 6, v5
	v_and_b32_e32 v7, 32, v7
	v_lshlrev_b32_e32 v2, 6, v2
	s_mov_b64 s[4:5], src_shared_base
	v_bitop3_b32 v5, v5, v7, v6 bitop3:0x36
	v_lshlrev_b32_e32 v11, 6, v1
	v_lshlrev_b32_e32 v3, 13, v3
	v_and_or_b32 v2, v2, s64, v6
	v_add_u32_e32 v8, s93, v5
	v_add_u32_e32 v148, 0xc000, v138
	v_mov_b32_e32 v149, s5
	v_add_u32_e32 v9, s96, v5
	v_add_u32_e32 v152, s93, v4
	v_mov_b32_e32 v153, s5
	v_mov_b32_e32 v139, s5
	v_add_u32_e32 v158, s96, v4
	v_mov_b32_e32 v159, s5
	v_add_u32_e32 v4, s46, v5
	v_add_u32_e32 v162, 0x4000, v138
	v_mov_b32_e32 v163, s5
	v_add_u32_e32 v10, s92, v5
	v_and_b32_e32 v11, 0x3000, v11
	v_add_u32_e32 v5, 0, v5
	v_xad_u32 v6, v2, v7, 0
	v_or_b32_e32 v7, 0x800, v3
	v_or_b32_e32 v12, 0x1000, v3
	v_or_b32_e32 v13, 0x1800, v3
	v_mov_b32_e32 v2, 0
	v_lshl_add_u64 v[150:151], v[148:149], 0, s[2:3]
	v_lshl_add_u64 v[154:155], v[152:153], 0, s[2:3]
	v_lshl_add_u64 v[156:157], v[138:139], 0, s[2:3]
	v_lshl_add_u64 v[160:161], v[158:159], 0, s[2:3]
	v_lshl_add_u64 v[164:165], v[162:163], 0, s[2:3]
	s_mov_b32 s18, -2
	v_add_u32_e32 v149, v8, v11
	v_add_u32_e32 v141, v5, v3
	v_add_u32_e32 v139, v6, v7
	v_add_u32_e32 v137, v6, v12
	v_add_u32_e32 v135, v6, v13
	v_add_u32_e32 v147, v9, v11
	v_add_u32_e32 v145, v4, v11
	v_add_u32_e32 v143, v10, v11
	s_mov_b64 s[4:5], s[78:79]
	v_mov_b64_e32 v[2:3], 0
	v_mov_b64_e32 v[4:5], 0
	v_mov_b64_e32 v[6:7], 0
	v_mov_b64_e32 v[8:9], 0
	v_mov_b64_e32 v[10:11], 0
	v_mov_b64_e32 v[12:13], 0
	v_mov_b64_e32 v[14:15], 0
	v_mov_b64_e32 v[16:17], 0
	v_mov_b64_e32 v[18:19], 0
	v_mov_b64_e32 v[20:21], 0
	v_mov_b64_e32 v[22:23], 0
	v_mov_b64_e32 v[24:25], 0
	v_mov_b64_e32 v[26:27], 0
	v_mov_b64_e32 v[28:29], 0
	v_mov_b64_e32 v[30:31], 0
	v_mov_b64_e32 v[32:33], 0
	v_mov_b64_e32 v[34:35], 0
	v_mov_b64_e32 v[36:37], 0
	v_mov_b64_e32 v[38:39], 0
	v_mov_b64_e32 v[40:41], 0
	v_mov_b64_e32 v[42:43], 0
	v_mov_b64_e32 v[44:45], 0
	v_mov_b64_e32 v[46:47], 0
	v_mov_b64_e32 v[48:49], 0
	v_mov_b64_e32 v[50:51], 0
	v_mov_b64_e32 v[52:53], 0
	v_mov_b64_e32 v[54:55], 0
	v_mov_b64_e32 v[56:57], 0
	v_mov_b64_e32 v[58:59], 0
	v_mov_b64_e32 v[60:61], 0
	v_mov_b64_e32 v[62:63], 0
	v_mov_b64_e32 v[64:65], 0
	v_mov_b64_e32 v[66:67], 0
	v_mov_b64_e32 v[68:69], 0
	v_mov_b64_e32 v[70:71], 0
	v_mov_b64_e32 v[72:73], 0
	v_mov_b64_e32 v[74:75], 0
	v_mov_b64_e32 v[76:77], 0
	v_mov_b64_e32 v[78:79], 0
	v_mov_b64_e32 v[80:81], 0
	v_mov_b64_e32 v[82:83], 0
	v_mov_b64_e32 v[84:85], 0
	v_mov_b64_e32 v[86:87], 0
	v_mov_b64_e32 v[88:89], 0
	v_mov_b64_e32 v[90:91], 0
	v_mov_b64_e32 v[92:93], 0
	v_mov_b64_e32 v[94:95], 0
	v_mov_b64_e32 v[96:97], 0
	v_mov_b64_e32 v[98:99], 0
	v_mov_b64_e32 v[100:101], 0
	v_mov_b64_e32 v[102:103], 0
	v_mov_b64_e32 v[104:105], 0
	v_mov_b64_e32 v[106:107], 0
	v_mov_b64_e32 v[108:109], 0
	v_mov_b64_e32 v[110:111], 0
	v_mov_b64_e32 v[112:113], 0
	v_mov_b64_e32 v[114:115], 0
	v_mov_b64_e32 v[116:117], 0
	v_mov_b64_e32 v[118:119], 0
	v_mov_b64_e32 v[120:121], 0
	v_mov_b64_e32 v[122:123], 0
	v_mov_b64_e32 v[124:125], 0
	v_mov_b64_e32 v[126:127], 0
	v_mov_b64_e32 v[128:129], 0
	s_barrier

;   #define WAIT_V(n) asm volatile("s_waitcnt vmcnt(" #n ")":::"memory")
;   #define BAR __builtin_amdgcn_s_barrier()
; template <bool TWO, class MID> ...
;     ...
;   int r0, c0, r1, c1; stage_rc(tid * 16, r0, c0); stage_rc(tid * 16 + 8192, r1, c1);
;   aoff0 = (unsigned)(r0 * lda + c0) * 2u; aoff1 = (unsigned)(r1 * lda + c1) * 2u;
;   boff0 = (unsigned)(r0 * ldb + c0) * 2u; boff1 = (unsigned)(r1 * ldb + c1) * 2u;
;   const char* Ab = (const char*)A + (size_t)brow * lda * 2;
;   const char* Bb = (const char*)Bt + (size_t)bcol * ldb * 2;
;   const char* Ab2 = TWO ? (const char*)A2 + (size_t)brow * lda2 * 2 : nullptr;
;   const char* Bb2 = TWO ? (const char*)Bt2 + (size_t)bcol * ldb2 * 2 : nullptr;
;     ...
;   const int wid = tid >> 6, lane = tid & 63, wr = wid >> 2, wc = wid & 3, fr = lane & 15, fq = lane >> 4;
;   bf16x8 At[4][2], B0[2][2], B1[2][2];
;   const int nt = K / BK;
;   if(wr==1)BAR;
;   if (fresh) WAIT_V(4);
;   BAR;
; template <int EPI>
; __device__ void gemm_phase(const bf16* A, int lda, const bf16* Bt, int K, int N, const Params& p, bool last, bf16* dstb, bf16* shm, unsigned long long* SSQ, int wv, const float* gbias = nullptr) {
;     ...
;     f32x4 acc[2][2][4][2] = {};
.LBB0_561:
	v_and_b32_e32 v5, 15, v2
	v_lshlrev_b32_e32 v7, 2, v2
	v_and_b32_e32 v6, 48, v2
	v_lshlrev_b32_e32 v5, 6, v5
	v_and_b32_e32 v7, 32, v7
	v_lshlrev_b32_e32 v2, 6, v2
	s_mov_b64 s[4:5], src_shared_base
	v_bitop3_b32 v5, v5, v7, v6 bitop3:0x36
	v_lshlrev_b32_e32 v11, 6, v1
	v_lshlrev_b32_e32 v3, 13, v3
	v_and_or_b32 v2, v2, s64, v6
	v_add_u32_e32 v8, s93, v5
	v_add_u32_e32 v148, 0xc000, v138
	v_mov_b32_e32 v149, s5
	v_add_u32_e32 v9, s96, v5
	v_add_u32_e32 v152, s93, v4
	v_mov_b32_e32 v153, s5
	v_mov_b32_e32 v139, s5
	v_add_u32_e32 v158, s96, v4
	v_mov_b32_e32 v159, s5
	v_add_u32_e32 v4, s46, v5
	v_add_u32_e32 v162, 0x4000, v138
	v_mov_b32_e32 v163, s5
	v_add_u32_e32 v10, s92, v5
	v_and_b32_e32 v11, 0x3000, v11
	v_add_u32_e32 v5, 0, v5
	v_xad_u32 v6, v2, v7, 0
	v_or_b32_e32 v7, 0x800, v3
	v_or_b32_e32 v12, 0x1000, v3
	v_or_b32_e32 v13, 0x1800, v3
	v_mov_b32_e32 v2, 0
	v_lshl_add_u64 v[150:151], v[148:149], 0, s[2:3]
	v_lshl_add_u64 v[154:155], v[152:153], 0, s[2:3]
	v_lshl_add_u64 v[156:157], v[138:139], 0, s[2:3]
	v_lshl_add_u64 v[160:161], v[158:159], 0, s[2:3]
	v_lshl_add_u64 v[164:165], v[162:163], 0, s[2:3]
	s_mov_b32 s22, -2
	v_add_u32_e32 v149, v8, v11
	v_add_u32_e32 v141, v5, v3
	v_add_u32_e32 v139, v6, v7
	v_add_u32_e32 v137, v6, v12
	v_add_u32_e32 v135, v6, v13
	v_add_u32_e32 v147, v9, v11
	v_add_u32_e32 v145, v4, v11
	v_add_u32_e32 v143, v10, v11
	s_mov_b64 s[4:5], s[78:79]
	v_mov_b64_e32 v[2:3], 0
	v_mov_b64_e32 v[4:5], 0
	v_mov_b64_e32 v[6:7], 0
	v_mov_b64_e32 v[8:9], 0
	v_mov_b64_e32 v[10:11], 0
	v_mov_b64_e32 v[12:13], 0
	v_mov_b64_e32 v[14:15], 0
	v_mov_b64_e32 v[16:17], 0
	v_mov_b64_e32 v[18:19], 0
	v_mov_b64_e32 v[20:21], 0
	v_mov_b64_e32 v[22:23], 0
	v_mov_b64_e32 v[24:25], 0
	v_mov_b64_e32 v[26:27], 0
	v_mov_b64_e32 v[28:29], 0
	v_mov_b64_e32 v[30:31], 0
	v_mov_b64_e32 v[32:33], 0
	v_mov_b64_e32 v[34:35], 0
	v_mov_b64_e32 v[36:37], 0
	v_mov_b64_e32 v[38:39], 0
	v_mov_b64_e32 v[40:41], 0
	v_mov_b64_e32 v[42:43], 0
	v_mov_b64_e32 v[44:45], 0
	v_mov_b64_e32 v[46:47], 0
	v_mov_b64_e32 v[48:49], 0
	v_mov_b64_e32 v[50:51], 0
	v_mov_b64_e32 v[52:53], 0
	v_mov_b64_e32 v[54:55], 0
	v_mov_b64_e32 v[56:57], 0
	v_mov_b64_e32 v[58:59], 0
	v_mov_b64_e32 v[60:61], 0
	v_mov_b64_e32 v[62:63], 0
	v_mov_b64_e32 v[64:65], 0
	v_mov_b64_e32 v[66:67], 0
	v_mov_b64_e32 v[68:69], 0
	v_mov_b64_e32 v[70:71], 0
	v_mov_b64_e32 v[72:73], 0
	v_mov_b64_e32 v[74:75], 0
	v_mov_b64_e32 v[76:77], 0
	v_mov_b64_e32 v[78:79], 0
	v_mov_b64_e32 v[80:81], 0
	v_mov_b64_e32 v[82:83], 0
	v_mov_b64_e32 v[84:85], 0
	v_mov_b64_e32 v[86:87], 0
	v_mov_b64_e32 v[88:89], 0
	v_mov_b64_e32 v[90:91], 0
	v_mov_b64_e32 v[92:93], 0
	v_mov_b64_e32 v[94:95], 0
	v_mov_b64_e32 v[96:97], 0
	v_mov_b64_e32 v[98:99], 0
	v_mov_b64_e32 v[100:101], 0
	v_mov_b64_e32 v[102:103], 0
	v_mov_b64_e32 v[104:105], 0
	v_mov_b64_e32 v[106:107], 0
	v_mov_b64_e32 v[108:109], 0
	v_mov_b64_e32 v[110:111], 0
	v_mov_b64_e32 v[112:113], 0
	v_mov_b64_e32 v[114:115], 0
	v_mov_b64_e32 v[116:117], 0
	v_mov_b64_e32 v[118:119], 0
	v_mov_b64_e32 v[120:121], 0
	v_mov_b64_e32 v[122:123], 0
	v_mov_b64_e32 v[124:125], 0
	v_mov_b64_e32 v[126:127], 0
	v_mov_b64_e32 v[128:129], 0
	s_barrier

; template <bool TWO, class MID> ...
;     ...
;   int r0, c0, r1, c1; stage_rc(tid * 16, r0, c0); stage_rc(tid * 16 + 8192, r1, c1);
;   aoff0 = (unsigned)(r0 * lda + c0) * 2u; aoff1 = (unsigned)(r1 * lda + c1) * 2u;
;   boff0 = (unsigned)(r0 * ldb + c0) * 2u; boff1 = (unsigned)(r1 * ldb + c1) * 2u;
;   const char* Ab = (const char*)A + (size_t)brow * lda * 2;
;   const char* Bb = (const char*)Bt + (size_t)bcol * ldb * 2;
;   const char* Ab2 = TWO ? (const char*)A2 + (size_t)brow * lda2 * 2 : nullptr;
;   const char* Bb2 = TWO ? (const char*)Bt2 + (size_t)bcol * ldb2 * 2 : nullptr;
;     ...
;   const int wid = tid >> 6, lane = tid & 63, wr = wid >> 2, wc = wid & 3, fr = lane & 15, fq = lane >> 4;
; template <int EPI>
; __device__ void gemm_phase(const bf16* A, int lda, const bf16* Bt, int K, int N, const Params& p, bool last, bf16* dstb, bf16* shm, unsigned long long* SSQ, int wv, const float* gbias = nullptr) {
;     ...
;     const int brow = pm * BM, bcol = pn * BM;
;     int tid = ltid(wv);
;     f32x4 acc[2][2][4][2] = {};
;     gemm_mainloop(acc, A, lda, Bt, K, K, brow, bcol, shm, tid, fresh, EPI != EPI_RESID);
.LBB0_619:
	v_and_b32_e32 v5, 15, v2
	v_lshlrev_b32_e32 v7, 2, v2
	v_and_b32_e32 v6, 48, v2
	v_lshlrev_b32_e32 v5, 6, v5
	v_and_b32_e32 v7, 32, v7
	v_lshlrev_b32_e32 v2, 6, v2
	s_mov_b64 s[0:1], src_shared_base
	v_bitop3_b32 v5, v5, v7, v6 bitop3:0x36
	v_lshlrev_b32_e32 v11, 6, v1
	v_lshlrev_b32_e32 v3, 13, v3
	v_and_or_b32 v2, v2, s64, v6
	v_add_u32_e32 v8, s93, v5
	v_add_u32_e32 v148, 0xc000, v138
	v_mov_b32_e32 v149, s1
	v_add_u32_e32 v9, s96, v5
	v_add_u32_e32 v152, s93, v4
	v_mov_b32_e32 v153, s1
	v_mov_b32_e32 v139, s1
	v_add_u32_e32 v158, s96, v4
	v_mov_b32_e32 v159, s1
	v_add_u32_e32 v4, s46, v5
	v_add_u32_e32 v162, 0x4000, v138
	v_mov_b32_e32 v163, s1
	v_add_u32_e32 v10, s92, v5
	v_and_b32_e32 v11, 0x3000, v11
	v_add_u32_e32 v5, 0, v5
	v_xad_u32 v6, v2, v7, 0
	v_or_b32_e32 v7, 0x800, v3
	v_or_b32_e32 v12, 0x1000, v3
	v_or_b32_e32 v13, 0x1800, v3
	v_mov_b32_e32 v2, 0
	v_lshl_add_u64 v[150:151], v[148:149], 0, s[2:3]
	v_lshl_add_u64 v[154:155], v[152:153], 0, s[2:3]
	v_lshl_add_u64 v[156:157], v[138:139], 0, s[2:3]
	v_lshl_add_u64 v[160:161], v[158:159], 0, s[2:3]
	v_lshl_add_u64 v[164:165], v[162:163], 0, s[2:3]
	s_mov_b32 s14, -2
	v_add_u32_e32 v149, v8, v11
	v_add_u32_e32 v141, v5, v3
	v_add_u32_e32 v139, v6, v7
	v_add_u32_e32 v137, v6, v12
	v_add_u32_e32 v135, v6, v13
	v_add_u32_e32 v147, v9, v11
	v_add_u32_e32 v145, v4, v11
	v_add_u32_e32 v143, v10, v11
	s_mov_b64 s[0:1], s[78:79]
	v_mov_b64_e32 v[2:3], 0
	v_mov_b64_e32 v[4:5], 0
	v_mov_b64_e32 v[6:7], 0
	v_mov_b64_e32 v[8:9], 0
	v_mov_b64_e32 v[10:11], 0
	v_mov_b64_e32 v[12:13], 0
	v_mov_b64_e32 v[14:15], 0
	v_mov_b64_e32 v[16:17], 0
	v_mov_b64_e32 v[18:19], 0
	v_mov_b64_e32 v[20:21], 0
	v_mov_b64_e32 v[22:23], 0
	v_mov_b64_e32 v[24:25], 0
	v_mov_b64_e32 v[26:27], 0
	v_mov_b64_e32 v[28:29], 0
	v_mov_b64_e32 v[30:31], 0
	v_mov_b64_e32 v[32:33], 0
	v_mov_b64_e32 v[34:35], 0
	v_mov_b64_e32 v[36:37], 0
	v_mov_b64_e32 v[38:39], 0
	v_mov_b64_e32 v[40:41], 0
	v_mov_b64_e32 v[42:43], 0
	v_mov_b64_e32 v[44:45], 0
	v_mov_b64_e32 v[46:47], 0
	v_mov_b64_e32 v[48:49], 0
	v_mov_b64_e32 v[50:51], 0
	v_mov_b64_e32 v[52:53], 0
	v_mov_b64_e32 v[54:55], 0
	v_mov_b64_e32 v[56:57], 0
	v_mov_b64_e32 v[58:59], 0
	v_mov_b64_e32 v[60:61], 0
	v_mov_b64_e32 v[62:63], 0
	v_mov_b64_e32 v[64:65], 0
	v_mov_b64_e32 v[66:67], 0
	v_mov_b64_e32 v[68:69], 0
	v_mov_b64_e32 v[70:71], 0
	v_mov_b64_e32 v[72:73], 0
	v_mov_b64_e32 v[74:75], 0
	v_mov_b64_e32 v[76:77], 0
	v_mov_b64_e32 v[78:79], 0
	v_mov_b64_e32 v[80:81], 0
	v_mov_b64_e32 v[82:83], 0
	v_mov_b64_e32 v[84:85], 0
	v_mov_b64_e32 v[86:87], 0
	v_mov_b64_e32 v[88:89], 0
	v_mov_b64_e32 v[90:91], 0
	v_mov_b64_e32 v[92:93], 0
	v_mov_b64_e32 v[94:95], 0
	v_mov_b64_e32 v[96:97], 0
	v_mov_b64_e32 v[98:99], 0
	v_mov_b64_e32 v[100:101], 0
	v_mov_b64_e32 v[102:103], 0
	v_mov_b64_e32 v[104:105], 0
	v_mov_b64_e32 v[106:107], 0
	v_mov_b64_e32 v[108:109], 0
	v_mov_b64_e32 v[110:111], 0
	v_mov_b64_e32 v[112:113], 0
	v_mov_b64_e32 v[114:115], 0
	v_mov_b64_e32 v[116:117], 0
	v_mov_b64_e32 v[118:119], 0
	v_mov_b64_e32 v[120:121], 0
	v_mov_b64_e32 v[122:123], 0
	v_mov_b64_e32 v[124:125], 0
	v_mov_b64_e32 v[126:127], 0
	v_mov_b64_e32 v[128:129], 0
	s_barrier
